# MLA loop: per-step load predicate inverted with s_not_b64 instead of v_cndmask+v_cmp (2 VALU and a VALU->SGPR dependency fewer per iteration)
# speedup vs baseline: 1.0071x; 1.0001x over previous
; #define LAS __attribute__((address_space(3)))
; DI unsigned pk2(float a, float b) { f32x2 v = {a, b}; bf16x2_t r = __builtin_convertvector(v, bf16x2_t); return __builtin_bit_cast(unsigned, r); }
; DI f32x16 mfma(bf16x8 a, bf16x8 b, f32x16 c) { return __builtin_amdgcn_mfma_f32_32x32x16_bf16(a, b, c, 0, 0, 0); }
; DI float ex2(float x) { return __builtin_amdgcn_exp2f(x); }
; template <int DQK>
; DI void attn_unit(int tid, char* lds, const u16* Qp, const u16* K1, const u16* V1, int nt1, int kpos0, const u16* K2, const u16* V2, int nt2, int qpos0, bool mask, float m_init, float l_init, u16* Op) {
;     ...
;     float ls = 0.f;
; #pragma unroll
;     for (int r = 0; r < 16; ++r) { c0[r] = ex2(c0[r]); c1[r] = ex2(c1[r]); ls += c0[r] + c1[r]; }
;     lrun += ls;
;     bf16x8 pb[4];
;     { u32x4 w = {pk2(c0[0], c0[1]), pk2(c0[2], c0[3]), pk2(c0[4], c0[5]), pk2(c0[6], c0[7])}; pb[0] = __builtin_bit_cast(bf16x8, w); }
;     { u32x4 w = {pk2(c0[8], c0[9]), pk2(c0[10], c0[11]), pk2(c0[12], c0[13]), pk2(c0[14], c0[15])}; pb[1] = __builtin_bit_cast(bf16x8, w); }
;     { u32x4 w = {pk2(c1[0], c1[1]), pk2(c1[2], c1[3]), pk2(c1[4], c1[5]), pk2(c1[6], c1[7])}; pb[2] = __builtin_bit_cast(bf16x8, w); }
;     { u32x4 w = {pk2(c1[8], c1[9]), pk2(c1[10], c1[11]), pk2(c1[12], c1[13]), pk2(c1[14], c1[15])}; pb[3] = __builtin_bit_cast(bf16x8, w); }
;     LAS char* Vb = (LAS char*)(lds + s_cur * SB + KB + vrb);
; #pragma unroll
;     for (int ks = 0; ks < 4; ++ks) {
;       const s16x4 l0 = __builtin_amdgcn_ds_read_tr16_b64_v4i16((LAS s16x4*)(Vb + ((2 * ks) * 2 + 0) * 512));
;       const s16x4 h0 = __builtin_amdgcn_ds_read_tr16_b64_v4i16((LAS s16x4*)(Vb + ((2 * ks + 1) * 2 + 0) * 512));
;       const s16x4 l1 = __builtin_amdgcn_ds_read_tr16_b64_v4i16((LAS s16x4*)(Vb + ((2 * ks) * 2 + 1) * 512));
;       const s16x4 h1 = __builtin_amdgcn_ds_read_tr16_b64_v4i16((LAS s16x4*)(Vb + ((2 * ks + 1) * 2 + 1) * 512));
;       const bf16x8 va0 = {l0[0], l0[1], l0[2], l0[3], h0[0], h0[1], h0[2], h0[3]};
;       const bf16x8 va1 = {l1[0], l1[1], l1[2], l1[3], h1[0], h1[1], h1[2], h1[3]};
;       o0 = mfma(va0, pb[ks], o0); o1 = mfma(va1, pb[ks], o1);
;     }
;     }
;     if (has_wr) sw(s_wr);
.LBB0_684:
.LBB0_685:
	s_mul_i32 s0, s20, 0x5400
	s_add_i32 s26, s0, 0
	v_add_u32_e32 v0, s26, v241
	v_exp_f32_e32 v130, v50
	v_exp_f32_e32 v146, v66
	v_exp_f32_e32 v131, v51
	v_exp_f32_e32 v147, v67
	v_exp_f32_e32 v132, v52
	v_exp_f32_e32 v148, v68
	v_exp_f32_e32 v133, v53
	v_exp_f32_e32 v149, v69
	v_exp_f32_e32 v134, v54
	v_exp_f32_e32 v150, v70
	v_exp_f32_e32 v135, v55
	v_exp_f32_e32 v151, v71
	v_exp_f32_e32 v136, v56
	v_exp_f32_e32 v152, v72
	v_exp_f32_e32 v137, v57
	v_exp_f32_e32 v153, v73
	ds_read_b64_tr_b16 v[66:67], v0 offset:13568
	ds_read_b64_tr_b16 v[68:69], v0 offset:14592
	ds_read_b64_tr_b16 v[70:71], v0 offset:14080
	ds_read_b64_tr_b16 v[72:73], v0 offset:15104
	v_exp_f32_e32 v142, v62
	v_exp_f32_e32 v143, v63
	v_exp_f32_e32 v144, v64
	v_exp_f32_e32 v145, v65
	v_cvt_pk_bf16_f32 v62, v130, v131
	v_cvt_pk_bf16_f32 v63, v132, v133
	v_cvt_pk_bf16_f32 v64, v134, v135
	v_cvt_pk_bf16_f32 v65, v136, v137
	v_exp_f32_e32 v138, v58
	v_exp_f32_e32 v139, v59
	s_waitcnt lgkmcnt(2)
	v_mfma_f32_32x32x16_bf16 v[18:33], v[66:69], v[62:65], v[18:33]
	v_exp_f32_e32 v140, v60
	v_exp_f32_e32 v141, v61
	v_cvt_pk_bf16_f32 v58, v138, v139
	v_cvt_pk_bf16_f32 v60, v142, v143
	v_cvt_pk_bf16_f32 v61, v144, v145
	v_cvt_pk_bf16_f32 v59, v140, v141
	v_cvt_pk_bf16_f32 v54, v146, v147
	s_waitcnt lgkmcnt(0)
	v_mfma_f32_32x32x16_bf16 v[2:17], v[70:73], v[62:65], v[2:17]
	ds_read_b64_tr_b16 v[62:63], v0 offset:15616
	ds_read_b64_tr_b16 v[64:65], v0 offset:16640
	ds_read_b64_tr_b16 v[66:67], v0 offset:16128
	ds_read_b64_tr_b16 v[68:69], v0 offset:17152
	v_cvt_pk_bf16_f32 v55, v148, v149
	v_cvt_pk_bf16_f32 v56, v150, v151
	v_cvt_pk_bf16_f32 v57, v152, v153
	v_exp_f32_e32 v154, v74
	v_exp_f32_e32 v155, v75
	v_exp_f32_e32 v156, v76
	s_waitcnt lgkmcnt(2)
	v_mfma_f32_32x32x16_bf16 v[18:33], v[62:65], v[58:61], v[18:33]
	v_exp_f32_e32 v157, v77
	v_exp_f32_e32 v158, v78
	v_exp_f32_e32 v159, v79
	v_exp_f32_e32 v160, v80
	v_exp_f32_e32 v161, v81
	v_cvt_pk_bf16_f32 v50, v154, v155
	v_cvt_pk_bf16_f32 v51, v156, v157
	s_waitcnt lgkmcnt(0)
	v_mfma_f32_32x32x16_bf16 v[2:17], v[66:69], v[58:61], v[2:17]
	ds_read_b64_tr_b16 v[58:59], v0 offset:17664
	ds_read_b64_tr_b16 v[60:61], v0 offset:18688
	ds_read_b64_tr_b16 v[62:63], v0 offset:18176
	ds_read_b64_tr_b16 v[64:65], v0 offset:19200
	v_cvt_pk_bf16_f32 v52, v158, v159
	v_cvt_pk_bf16_f32 v53, v160, v161
	s_andn2_b64 vcc, exec, s[16:17]
	s_mul_i32 s27, s23, 0x5400
	s_waitcnt lgkmcnt(2)
	v_mfma_f32_32x32x16_bf16 v[18:33], v[58:61], v[54:57], v[18:33]
	s_waitcnt lgkmcnt(0)
	v_mfma_f32_32x32x16_bf16 v[2:17], v[62:65], v[54:57], v[2:17]
	ds_read_b64_tr_b16 v[54:55], v0 offset:19712
	ds_read_b64_tr_b16 v[56:57], v0 offset:20736
	ds_read_b64_tr_b16 v[58:59], v0 offset:20224
	ds_read_b64_tr_b16 v[60:61], v0 offset:21248
	s_not_b64 s[0:1], s[16:17]
	s_waitcnt lgkmcnt(2)
	v_mfma_f32_32x32x16_bf16 v[18:33], v[54:57], v[50:53], v[18:33]
	s_waitcnt lgkmcnt(0)
	v_mfma_f32_32x32x16_bf16 v[2:17], v[58:61], v[50:53], v[2:17]
	s_cbranch_vccnz .LBB0_689
	s_add_i32 s28, s27, 0
	v_add_u32_e32 v0, s28, v246
	s_waitcnt vmcnt(2)
	ds_write_b128 v0, v[186:189] offset:256
	s_and_saveexec_b64 s[16:17], s[8:9]
	s_cbranch_execz .LBB0_688
	v_add_u32_e32 v0, s28, v245
	s_waitcnt vmcnt(1)
	ds_write_b128 v0, v[190:193] offset:256
